# gdn prep: the 16 per-token l2-norm wave sums use DPP quad_perm/row_mirror and permlane16/32 swap steps instead of ds_bpermute round trips (same summation tree, bit-identical); on top of the forward-su
# baseline (speedup 1.0000x reference)
; #define LAS __attribute__((address_space(3)))
; DI unsigned pk2(float lo, float hi) { f32x2 v = {lo, hi}; bf16x2_t b = __builtin_convertvector(v, bf16x2_t); return __builtin_bit_cast(unsigned, b); }
; DI float lo_bf(unsigned u) { return __uint_as_float(u << 16); }
; DI float hi_bf(unsigned u) { return __uint_as_float(u & 0xffff0000u); }
; DI float siluf_(float x) { return x * __builtin_amdgcn_rcpf(1.f + __expf(-x)); }
; DI void gdn_prep_item(LAS unsigned char* lds, const Ctx& c, int l, int item) {
;     ...
;             for (int r = 0; r < 11; ++r) { x0[r] = lo_bf(xin[which][r]); x1[r] = hi_bf(xin[which][r]); }
; #pragma unroll
;             for (int t = 0; t < 8; ++t) {
;                 float a0 = 0.f, a1 = 0.f;
; #pragma unroll
;                 for (int j = 0; j < 4; ++j) { a0 += w0[j] * x0[t + j]; a1 += w1[j] * x1[t + j]; }
;                 a0 = siluf_(a0); a1 = siluf_(a1);
;                 const int tl = 8 * tg + t;
;                 if (which < 2) {
;                     const float ss = wave_sum(a0 * a0 + a1 * a1); float rs = __builtin_amdgcn_rsqf(ss + RMS_EPS); if (which == 0) rs *= 0.08838834764831845f;
;                     a0 *= rs; a1 *= rs;
;                     *(LAS unsigned*)(lds + (which == 0 ? GP_QB : GP_KB) + tl * 272 + cp * 4) = pk2(a0, a1);
.LBB0_278:
	v_lshlrev_b32_e32 v0, 2, v0
	v_lshl_add_u64 v[8:9], s[72:73], 0, v[0:1]
	v_add_co_u32_e32 v4, vcc, 0x1000, v8
	s_waitcnt vmcnt(8)
	v_and_b32_e32 v81, 0xffff0000, v61
	v_addc_co_u32_e32 v5, vcc, 0, v9, vcc
	v_add_co_u32_e32 v6, vcc, 0x3000, v8
	v_lshlrev_b32_e32 v80, 16, v61
	s_nop 0
	v_addc_co_u32_e32 v7, vcc, 0, v9, vcc
	v_add_co_u32_e32 v8, vcc, s63, v8
	v_and_b32_e32 v61, 64, v230
	s_nop 0
	v_addc_co_u32_e32 v9, vcc, 0, v9, vcc
	v_lshlrev_b32_e32 v44, 16, v32
	v_and_b32_e32 v45, 0xffff0000, v32
	v_lshlrev_b32_e32 v40, 16, v33
	v_and_b32_e32 v41, 0xffff0000, v33
	v_lshlrev_b32_e32 v32, 16, v62
	v_and_b32_e32 v33, 0xffff0000, v62
	v_add_u32_e32 v61, 64, v61
	v_xor_b32_e32 v62, 1, v230
	v_cmp_lt_i32_e32 vcc, v62, v61
	v_lshlrev_b32_e32 v48, 16, v31
	v_and_b32_e32 v49, 0xffff0000, v31
	v_cndmask_b32_e32 v62, v230, v62, vcc
	v_lshlrev_b32_e32 v66, 2, v62
	v_xor_b32_e32 v62, 2, v230
	v_cmp_lt_i32_e32 vcc, v62, v61
	s_waitcnt vmcnt(7)
	v_pk_fma_f32 v[80:81], v[18:19], v[80:81], 0 op_sel_hi:[1,1,0]
	v_lshlrev_b32_e32 v46, 16, v30
	v_cndmask_b32_e32 v62, v230, v62, vcc
	v_lshlrev_b32_e32 v65, 2, v62
	v_xor_b32_e32 v62, 4, v230
	v_cmp_lt_i32_e32 vcc, v62, v61
	v_and_b32_e32 v47, 0xffff0000, v30
	v_lshlrev_b32_e32 v42, 16, v34
	v_cndmask_b32_e32 v62, v230, v62, vcc
	v_lshlrev_b32_e32 v64, 2, v62
	v_xor_b32_e32 v62, 8, v230
	v_cmp_lt_i32_e32 vcc, v62, v61
	v_and_b32_e32 v43, 0xffff0000, v34
	v_lshlrev_b32_e32 v38, 16, v36
	v_cndmask_b32_e32 v62, v230, v62, vcc
	v_and_b32_e32 v39, 0xffff0000, v36
	v_lshlrev_b32_e32 v30, 16, v35
	v_and_b32_e32 v31, 0xffff0000, v35
	v_lshlrev_b32_e32 v34, 16, v37
	v_and_b32_e32 v35, 0xffff0000, v37
	v_lshlrev_b32_e32 v36, 16, v63
	v_and_b32_e32 v37, 0xffff0000, v63
	v_lshlrev_b32_e32 v63, 2, v62
	v_xor_b32_e32 v62, 16, v230
	s_waitcnt vmcnt(6)
	v_pk_fma_f32 v[80:81], v[20:21], v[48:49], v[80:81]
	v_cmp_lt_i32_e32 vcc, v62, v61
	v_xor_b32_e32 v79, 32, v230
	s_waitcnt vmcnt(5)
	v_pk_fma_f32 v[80:81], v[22:23], v[46:47], v[80:81]
	v_cndmask_b32_e32 v62, v230, v62, vcc
	v_cmp_lt_i32_e32 vcc, v79, v61
	s_waitcnt vmcnt(4)
	v_pk_fma_f32 v[80:81], v[24:25], v[44:45], v[80:81]
	v_lshlrev_b32_e32 v62, 2, v62
	v_cndmask_b32_e32 v61, v230, v79, vcc
	v_mul_f32_e32 v79, 0xbfb8aa3b, v81
	v_exp_f32_e32 v79, v79
	v_lshlrev_b32_e32 v61, 2, v61
	s_lshr_b32 s4, s33, 2
	s_and_b32 s4, s4, 0x7f
	v_add_f32_e32 v79, 1.0, v79
	v_rcp_f32_e32 v83, v79
	v_mul_f32_e32 v79, 0xbfb8aa3b, v80
	v_exp_f32_e32 v79, v79
	global_load_dwordx2 v[2:3], v0, s[72:73]
	v_pk_fma_f32 v[48:49], v[18:19], v[48:49], 0 op_sel_hi:[1,1,0]
	global_load_dwordx2 v[4:5], v[4:5], off offset:2048
	v_add_f32_e32 v79, 1.0, v79
	v_rcp_f32_e32 v82, v79
	global_load_dwordx2 v[6:7], v[6:7], off
	s_lshl_b32 s10, s4, 13
	global_load_dwordx2 v[8:9], v[8:9], off offset:2048
	v_pk_mul_f32 v[80:81], v[80:81], v[82:83]
	v_lshlrev_b32_e32 v0, 2, v27
	v_pk_mul_f32 v[82:83], v[80:81], v[80:81]
	v_add_u32_e32 v28, 0, v0
	v_add_f32_e32 v79, v83, v82
	s_nop 1
	v_mov_b32_dpp v82, v79 quad_perm:[1,0,3,2] row_mask:0xf bank_mask:0xf
	v_readlane_b32 s4, v254, 4
	v_pk_fma_f32 v[48:49], v[20:21], v[46:47], v[48:49]
	v_add_u32_e32 v67, v28, v0
	v_lshl_add_u32 v0, v27, 3, s4
	s_waitcnt lgkmcnt(0)
	v_add_f32_e32 v79, v79, v82
	s_nop 1
	v_mov_b32_dpp v82, v79 quad_perm:[2,3,0,1] row_mask:0xf bank_mask:0xf
	s_mul_i32 s4, s83, 0x880
	v_pk_fma_f32 v[48:49], v[22:23], v[44:45], v[48:49]
	v_pk_fma_f32 v[46:47], v[18:19], v[46:47], 0 op_sel_hi:[1,1,0]
	v_pk_fma_f32 v[48:49], v[24:25], v[42:43], v[48:49]
	s_waitcnt lgkmcnt(0)
	v_add_f32_e32 v79, v79, v82
	s_nop 1
	v_mov_b32_dpp v82, v79 row_half_mirror row_mask:0xf bank_mask:0xf
	v_pk_fma_f32 v[46:47], v[20:21], v[44:45], v[46:47]
	v_pk_fma_f32 v[44:45], v[18:19], v[44:45], 0 op_sel_hi:[1,1,0]
	v_pk_fma_f32 v[46:47], v[22:23], v[42:43], v[46:47]
	v_pk_fma_f32 v[44:45], v[20:21], v[42:43], v[44:45]
	s_waitcnt lgkmcnt(0)
	v_add_f32_e32 v79, v79, v82
	s_nop 1
	v_mov_b32_dpp v82, v79 row_mirror row_mask:0xf bank_mask:0xf
	v_pk_fma_f32 v[46:47], v[24:25], v[40:41], v[46:47]
	v_pk_fma_f32 v[44:45], v[22:23], v[40:41], v[44:45]
	v_pk_fma_f32 v[42:43], v[18:19], v[42:43], 0 op_sel_hi:[1,1,0]
	v_pk_fma_f32 v[44:45], v[24:25], v[38:39], v[44:45]
	s_waitcnt lgkmcnt(0)
	v_add_f32_e32 v79, v79, v82
	v_mov_b32_e32 v82, v79
	v_mov_b32_e32 v89, v79
	s_nop 1
	v_permlane16_swap_b32_e32 v82, v89
	s_nop 1
	v_mov_b32_dpp v82, v89 quad_perm:[0,1,2,3] row_mask:0x5 bank_mask:0xf
	v_pk_fma_f32 v[42:43], v[20:21], v[40:41], v[42:43]
	v_pk_fma_f32 v[40:41], v[18:19], v[40:41], 0 op_sel_hi:[1,1,0]
	v_pk_fma_f32 v[42:43], v[22:23], v[38:39], v[42:43]
	v_pk_fma_f32 v[40:41], v[20:21], v[38:39], v[40:41]
	s_waitcnt lgkmcnt(0)
	v_add_f32_e32 v79, v79, v82
	v_mov_b32_e32 v82, v79
	v_mov_b32_e32 v89, v79
	s_nop 1
	v_permlane32_swap_b32_e32 v82, v89
	s_nop 1
	v_mov_b32_dpp v82, v89 quad_perm:[0,1,2,3] row_mask:0x3 bank_mask:0xf
	v_pk_fma_f32 v[42:43], v[24:25], v[30:31], v[42:43]
	v_pk_fma_f32 v[40:41], v[22:23], v[30:31], v[40:41]
	v_pk_fma_f32 v[38:39], v[18:19], v[38:39], 0 op_sel_hi:[1,1,0]
	v_pk_fma_f32 v[40:41], v[24:25], v[32:33], v[40:41]
	s_waitcnt lgkmcnt(0)
; #define LAS __attribute__((address_space(3)))
; DI unsigned pk2(float lo, float hi) { f32x2 v = {lo, hi}; bf16x2_t b = __builtin_convertvector(v, bf16x2_t); return __builtin_bit_cast(unsigned, b); }
; DI float siluf_(float x) { return x * __builtin_amdgcn_rcpf(1.f + __expf(-x)); }
; DI float wave_sum(float v) {
; #pragma unroll
;     for (int o = 1; o < 64; o <<= 1) v += __shfl_xor(v, o);
;     return v;
; }
; DI void gdn_prep_item(LAS unsigned char* lds, const Ctx& c, int l, int item) {
;     ...
;             for (int t = 0; t < 8; ++t) {
;                 float a0 = 0.f, a1 = 0.f;
; #pragma unroll
;                 for (int j = 0; j < 4; ++j) { a0 += w0[j] * x0[t + j]; a1 += w1[j] * x1[t + j]; }
;                 a0 = siluf_(a0); a1 = siluf_(a1);
;                 const int tl = 8 * tg + t;
;                 if (which < 2) {
;                     const float ss = wave_sum(a0 * a0 + a1 * a1); float rs = __builtin_amdgcn_rsqf(ss + RMS_EPS); if (which == 0) rs *= 0.08838834764831845f;
;                     a0 *= rs; a1 *= rs;
;                     *(LAS unsigned*)(lds + (which == 0 ? GP_QB : GP_KB) + tl * 272 + cp * 4) = pk2(a0, a1);
;                     if (which == 1) { kf[tl * 129 + 2 * cp] = a0; kf[tl * 129 + 2 * cp + 1] = a1; }
;                 } else { vf[tl * 129 + 2 * cp] = a0; vf[tl * 129 + 2 * cp + 1] = a1; }
;             }
;         }
	v_add_f32_e32 v79, v79, v82
	v_add_f32_e32 v79, 0x358637bd, v79
	v_rsq_f32_e32 v79, v79
	v_pk_fma_f32 v[38:39], v[20:21], v[30:31], v[38:39]
	v_pk_fma_f32 v[18:19], v[18:19], v[30:31], 0 op_sel_hi:[1,1,0]
	v_pk_fma_f32 v[38:39], v[22:23], v[32:33], v[38:39]
	v_mul_f32_e32 v82, 0x3db504f3, v79
	v_pk_mul_f32 v[80:81], v[80:81], v[82:83] op_sel_hi:[1,0]
	v_add_u32_e32 v79, s4, v28
	v_cvt_pk_bf16_f32 v80, v80, v81
	ds_write_b32 v79, v80
	v_mul_f32_e32 v80, 0xbfb8aa3b, v49
	v_exp_f32_e32 v80, v80
	s_or_b32 s4, s86, 1
	s_mul_i32 s5, s4, 0x110
	v_pk_fma_f32 v[38:39], v[24:25], v[34:35], v[38:39]
	v_add_f32_e32 v80, 1.0, v80
	v_rcp_f32_e32 v81, v80
	v_mul_f32_e32 v80, 0xbfb8aa3b, v48
	v_exp_f32_e32 v80, v80
	v_pk_fma_f32 v[18:19], v[20:21], v[32:33], v[18:19]
	s_mulk_i32 s83, 0x1020
	v_pk_fma_f32 v[18:19], v[22:23], v[34:35], v[18:19]
	v_add_f32_e32 v80, 1.0, v80
	v_rcp_f32_e32 v80, v80
	v_pk_fma_f32 v[18:19], v[24:25], v[36:37], v[18:19]
	v_lshlrev_b32_e32 v36, 16, v72
	v_and_b32_e32 v37, 0xffff0000, v72
	v_pk_mul_f32 v[48:49], v[48:49], v[80:81]
	v_mul_f32_e32 v20, 0xbfb8aa3b, v19
	v_pk_mul_f32 v[80:81], v[48:49], v[48:49]
	v_exp_f32_e32 v20, v20
	v_add_f32_e32 v80, v81, v80
	s_nop 1
	v_mov_b32_dpp v81, v80 quad_perm:[1,0,3,2] row_mask:0xf bank_mask:0xf
	v_lshlrev_b32_e32 v34, 16, v71
	v_add_f32_e32 v20, 1.0, v20
	v_rcp_f32_e32 v21, v20
	v_mul_f32_e32 v20, 0xbfb8aa3b, v18
	s_waitcnt lgkmcnt(0)
	v_add_f32_e32 v80, v80, v81
	s_nop 1
	v_mov_b32_dpp v81, v80 quad_perm:[2,3,0,1] row_mask:0xf bank_mask:0xf
	v_exp_f32_e32 v20, v20
	v_and_b32_e32 v35, 0xffff0000, v71
	s_mulk_i32 s4, 0x204
	v_lshlrev_b32_e32 v32, 16, v74
	s_waitcnt lgkmcnt(0)
	v_add_f32_e32 v80, v80, v81
	s_nop 1
	v_mov_b32_dpp v81, v80 row_half_mirror row_mask:0xf bank_mask:0xf
	v_add_f32_e32 v20, 1.0, v20
	v_rcp_f32_e32 v20, v20
	v_and_b32_e32 v33, 0xffff0000, v74
	v_lshlrev_b32_e32 v30, 16, v73
	s_waitcnt lgkmcnt(0)
	v_add_f32_e32 v80, v80, v81
	s_nop 1
	v_mov_b32_dpp v81, v80 row_mirror row_mask:0xf bank_mask:0xf
	v_pk_mul_f32 v[18:19], v[18:19], v[20:21]
	v_and_b32_e32 v31, 0xffff0000, v73
	v_pk_mul_f32 v[20:21], v[18:19], v[18:19]
	s_add_i32 s6, s4, 0x408
	s_waitcnt lgkmcnt(0)
	v_add_f32_e32 v80, v80, v81
	v_mov_b32_e32 v81, v80
	v_mov_b32_e32 v89, v80
	s_nop 1
	v_permlane16_swap_b32_e32 v81, v89
	s_nop 1
	v_mov_b32_dpp v81, v89 quad_perm:[0,1,2,3] row_mask:0x5 bank_mask:0xf
	v_add_f32_e32 v20, v21, v20
	s_nop 1
	v_mov_b32_dpp v21, v20 quad_perm:[1,0,3,2] row_mask:0xf bank_mask:0xf
	s_add_i32 s7, s4, 0x60c
	s_add_i32 s9, s4, 0x810
	s_waitcnt lgkmcnt(0)
	v_add_f32_e32 v80, v80, v81
	v_mov_b32_e32 v81, v80
	v_mov_b32_e32 v89, v80
	s_nop 1
	v_permlane32_swap_b32_e32 v81, v89
	s_nop 1
	v_mov_b32_dpp v81, v89 quad_perm:[0,1,2,3] row_mask:0x3 bank_mask:0xf
	s_waitcnt lgkmcnt(0)
	v_add_f32_e32 v20, v20, v21
	s_nop 1
	v_mov_b32_dpp v21, v20 quad_perm:[2,3,0,1] row_mask:0xf bank_mask:0xf
	v_lshlrev_b32_e32 v22, 16, v78
	v_and_b32_e32 v23, 0xffff0000, v78
	s_waitcnt lgkmcnt(0)
	v_add_f32_e32 v80, v80, v81
	v_add_f32_e32 v80, 0x358637bd, v80
	v_rsq_f32_e32 v80, v80
	s_waitcnt lgkmcnt(0)
	v_add_f32_e32 v20, v20, v21
	s_nop 1
	v_mov_b32_dpp v21, v20 row_half_mirror row_mask:0xf bank_mask:0xf
	v_lshlrev_b32_e32 v24, 16, v77
	v_mul_f32_e32 v80, 0x3db504f3, v80
	v_pk_mul_f32 v[48:49], v[48:49], v[80:81] op_sel_hi:[1,0]
	v_mul_f32_e32 v80, 0xbfb8aa3b, v47
	v_exp_f32_e32 v80, v80
	v_cvt_pk_bf16_f32 v49, v48, v49
	v_add_u32_e32 v48, s5, v28
	s_waitcnt lgkmcnt(0)
	v_add_f32_e32 v20, v20, v21
	v_add_f32_e32 v80, 1.0, v80
	v_rcp_f32_e32 v81, v80
	v_mul_f32_e32 v80, 0xbfb8aa3b, v46
	v_exp_f32_e32 v80, v80
	s_nop 1
	v_mov_b32_dpp v21, v20 row_mirror row_mask:0xf bank_mask:0xf
	s_add_i32 s5, s4, 0x204
	v_and_b32_e32 v25, 0xffff0000, v77
	v_add_f32_e32 v80, 1.0, v80
	v_rcp_f32_e32 v80, v80
	s_waitcnt lgkmcnt(0)
	v_add_f32_e32 v20, v20, v21
	v_mov_b32_e32 v21, v20
	v_mov_b32_e32 v89, v20
	s_nop 1
	v_permlane16_swap_b32_e32 v21, v89
	s_nop 1
	v_mov_b32_dpp v21, v89 quad_perm:[0,1,2,3] row_mask:0x5 bank_mask:0xf
	s_add_i32 s11, s4, 0xa14
	v_pk_mul_f32 v[46:47], v[46:47], v[80:81]
	s_add_i32 s14, s4, 0xc18
	v_pk_mul_f32 v[80:81], v[46:47], v[46:47]
	s_waitcnt lgkmcnt(0)
	v_add_f32_e32 v20, v20, v21
	v_add_f32_e32 v80, v81, v80
	s_nop 1
	v_mov_b32_dpp v81, v80 quad_perm:[1,0,3,2] row_mask:0xf bank_mask:0xf
	v_mov_b32_e32 v21, v20
	v_mov_b32_e32 v89, v20
	s_nop 1
	v_permlane32_swap_b32_e32 v21, v89
	s_nop 1
	v_mov_b32_dpp v21, v89 quad_perm:[0,1,2,3] row_mask:0x3 bank_mask:0xf
	s_and_b32 s8, s2, 3
	s_lshl_b32 s24, s84, 2
	s_bfe_u32 s43, s82, 0x20006
	s_waitcnt lgkmcnt(0)
	v_add_f32_e32 v80, v80, v81
	s_nop 1
	v_mov_b32_dpp v81, v80 quad_perm:[2,3,0,1] row_mask:0xf bank_mask:0xf
	s_waitcnt lgkmcnt(0)
	v_add_f32_e32 v20, v20, v21
	v_add_f32_e32 v20, 0x358637bd, v20
	v_rsq_f32_e32 v20, v20
	s_cmpk_gt_u32 s82, 0xff
	s_waitcnt lgkmcnt(0)
	v_add_f32_e32 v80, v80, v81
	s_nop 1
	v_mov_b32_dpp v81, v80 row_half_mirror row_mask:0xf bank_mask:0xf
	v_mul_f32_e32 v20, 0x3db504f3, v20
	v_pk_mul_f32 v[18:19], v[18:19], v[20:21] op_sel_hi:[1,0]
	v_lshlrev_b32_e32 v20, 16, v75
	v_cvt_pk_bf16_f32 v18, v18, v19
	s_waitcnt lgkmcnt(0)
	v_add_f32_e32 v80, v80, v81
	s_nop 1
	v_mov_b32_dpp v81, v80 row_mirror row_mask:0xf bank_mask:0xf
	v_and_b32_e32 v19, 0xffff0000, v76
	v_and_b32_e32 v21, 0xffff0000, v75
	s_waitcnt lgkmcnt(0)
	v_add_f32_e32 v80, v80, v81
	v_mov_b32_e32 v81, v80
	v_mov_b32_e32 v89, v80
	s_nop 1
	v_permlane16_swap_b32_e32 v81, v89
	s_nop 1
	v_mov_b32_dpp v81, v89 quad_perm:[0,1,2,3] row_mask:0x5 bank_mask:0xf
	s_waitcnt lgkmcnt(0)
; #define LAS __attribute__((address_space(3)))
; DI unsigned pk2(float lo, float hi) { f32x2 v = {lo, hi}; bf16x2_t b = __builtin_convertvector(v, bf16x2_t); return __builtin_bit_cast(unsigned, b); }
; DI float siluf_(float x) { return x * __builtin_amdgcn_rcpf(1.f + __expf(-x)); }
; DI float wave_sum(float v) {
; #pragma unroll
;     for (int o = 1; o < 64; o <<= 1) v += __shfl_xor(v, o);
;     return v;
; }
; DI void gdn_prep_item(LAS unsigned char* lds, const Ctx& c, int l, int item) {
;     ...
;             for (int t = 0; t < 8; ++t) {
;                 float a0 = 0.f, a1 = 0.f;
; #pragma unroll
;                 for (int j = 0; j < 4; ++j) { a0 += w0[j] * x0[t + j]; a1 += w1[j] * x1[t + j]; }
;                 a0 = siluf_(a0); a1 = siluf_(a1);
;                 const int tl = 8 * tg + t;
;                 if (which < 2) {
;                     const float ss = wave_sum(a0 * a0 + a1 * a1); float rs = __builtin_amdgcn_rsqf(ss + RMS_EPS); if (which == 0) rs *= 0.08838834764831845f;
;                     a0 *= rs; a1 *= rs;
;                     *(LAS unsigned*)(lds + (which == 0 ? GP_QB : GP_KB) + tl * 272 + cp * 4) = pk2(a0, a1);
;                     if (which == 1) { kf[tl * 129 + 2 * cp] = a0; kf[tl * 129 + 2 * cp + 1] = a1; }
;                 } else { vf[tl * 129 + 2 * cp] = a0; vf[tl * 129 + 2 * cp + 1] = a1; }
;             }
;         }
	v_add_f32_e32 v80, v80, v81
	v_mov_b32_e32 v81, v80
	v_mov_b32_e32 v89, v80
	s_nop 1
	v_permlane32_swap_b32_e32 v81, v89
	s_nop 1
	v_mov_b32_dpp v81, v89 quad_perm:[0,1,2,3] row_mask:0x3 bank_mask:0xf
	s_waitcnt lgkmcnt(0)
	v_add_f32_e32 v80, v80, v81
	v_add_f32_e32 v80, 0x358637bd, v80
	v_rsq_f32_e32 v80, v80
	s_nop 0
	v_mul_f32_e32 v80, 0x3db504f3, v80
	v_pk_mul_f32 v[46:47], v[46:47], v[80:81] op_sel_hi:[1,0]
	s_nop 0
	v_cvt_pk_bf16_f32 v46, v46, v47
	ds_write2_b32 v48, v49, v46 offset1:68
	v_mul_f32_e32 v46, 0xbfb8aa3b, v45
	v_exp_f32_e32 v46, v46
	s_nop 0
	v_add_f32_e32 v46, 1.0, v46
	v_rcp_f32_e32 v47, v46
	v_mul_f32_e32 v46, 0xbfb8aa3b, v44
	v_exp_f32_e32 v46, v46
	s_nop 0
	v_add_f32_e32 v46, 1.0, v46
	v_rcp_f32_e32 v46, v46
	s_nop 0
	v_pk_mul_f32 v[44:45], v[44:45], v[46:47]
	s_nop 0
	v_pk_mul_f32 v[46:47], v[44:45], v[44:45]
	s_nop 0
	v_add_f32_e32 v46, v47, v46
	s_nop 1
	v_mov_b32_dpp v47, v46 quad_perm:[1,0,3,2] row_mask:0xf bank_mask:0xf
	s_waitcnt lgkmcnt(0)
	v_add_f32_e32 v46, v46, v47
	s_nop 1
	v_mov_b32_dpp v47, v46 quad_perm:[2,3,0,1] row_mask:0xf bank_mask:0xf
	s_waitcnt lgkmcnt(0)
	v_add_f32_e32 v46, v46, v47
	s_nop 1
	v_mov_b32_dpp v47, v46 row_half_mirror row_mask:0xf bank_mask:0xf
	s_waitcnt lgkmcnt(0)
	v_add_f32_e32 v46, v46, v47
	s_nop 1
	v_mov_b32_dpp v47, v46 row_mirror row_mask:0xf bank_mask:0xf
	s_waitcnt lgkmcnt(0)
	v_add_f32_e32 v46, v46, v47
	v_mov_b32_e32 v47, v46
	v_mov_b32_e32 v89, v46
	s_nop 1
	v_permlane16_swap_b32_e32 v47, v89
	s_nop 1
	v_mov_b32_dpp v47, v89 quad_perm:[0,1,2,3] row_mask:0x5 bank_mask:0xf
	s_waitcnt lgkmcnt(0)
	v_add_f32_e32 v46, v46, v47
	v_mov_b32_e32 v47, v46
	v_mov_b32_e32 v89, v46
	s_nop 1
	v_permlane32_swap_b32_e32 v47, v89
	s_nop 1
	v_mov_b32_dpp v47, v89 quad_perm:[0,1,2,3] row_mask:0x3 bank_mask:0xf
	s_waitcnt lgkmcnt(0)
	v_add_f32_e32 v46, v46, v47
	v_add_f32_e32 v46, 0x358637bd, v46
	v_rsq_f32_e32 v46, v46
	s_nop 0
	v_mul_f32_e32 v46, 0x3db504f3, v46
	v_pk_mul_f32 v[44:45], v[44:45], v[46:47] op_sel_hi:[1,0]
	s_nop 0
	v_cvt_pk_bf16_f32 v46, v44, v45
	v_mul_f32_e32 v44, 0xbfb8aa3b, v43
	v_exp_f32_e32 v44, v44
	s_nop 0
	v_add_f32_e32 v44, 1.0, v44
	v_rcp_f32_e32 v45, v44
	v_mul_f32_e32 v44, 0xbfb8aa3b, v42
	v_exp_f32_e32 v44, v44
	s_nop 0
	v_add_f32_e32 v44, 1.0, v44
	v_rcp_f32_e32 v44, v44
	s_nop 0
	v_pk_mul_f32 v[42:43], v[42:43], v[44:45]
	s_nop 0
	v_pk_mul_f32 v[44:45], v[42:43], v[42:43]
	s_nop 0
	v_add_f32_e32 v44, v45, v44
	s_nop 1
	v_mov_b32_dpp v45, v44 quad_perm:[1,0,3,2] row_mask:0xf bank_mask:0xf
	s_waitcnt lgkmcnt(0)
	v_add_f32_e32 v44, v44, v45
	s_nop 1
	v_mov_b32_dpp v45, v44 quad_perm:[2,3,0,1] row_mask:0xf bank_mask:0xf
	s_waitcnt lgkmcnt(0)
	v_add_f32_e32 v44, v44, v45
	s_nop 1
	v_mov_b32_dpp v45, v44 row_half_mirror row_mask:0xf bank_mask:0xf
	s_waitcnt lgkmcnt(0)
	v_add_f32_e32 v44, v44, v45
	s_nop 1
	v_mov_b32_dpp v45, v44 row_mirror row_mask:0xf bank_mask:0xf
	s_waitcnt lgkmcnt(0)
	v_add_f32_e32 v44, v44, v45
	v_mov_b32_e32 v45, v44
	v_mov_b32_e32 v89, v44
	s_nop 1
	v_permlane16_swap_b32_e32 v45, v89
	s_nop 1
	v_mov_b32_dpp v45, v89 quad_perm:[0,1,2,3] row_mask:0x5 bank_mask:0xf
	s_waitcnt lgkmcnt(0)
	v_add_f32_e32 v44, v44, v45
	v_mov_b32_e32 v45, v44
	v_mov_b32_e32 v89, v44
	s_nop 1
	v_permlane32_swap_b32_e32 v45, v89
	s_nop 1
	v_mov_b32_dpp v45, v89 quad_perm:[0,1,2,3] row_mask:0x3 bank_mask:0xf
	s_waitcnt lgkmcnt(0)
	v_add_f32_e32 v44, v44, v45
	v_add_f32_e32 v44, 0x358637bd, v44
	v_rsq_f32_e32 v44, v44
	s_nop 0
	v_mul_f32_e32 v44, 0x3db504f3, v44
	v_pk_mul_f32 v[42:43], v[42:43], v[44:45] op_sel_hi:[1,0]
	s_nop 0
	v_cvt_pk_bf16_f32 v42, v42, v43
	ds_write2_b32 v48, v46, v42 offset0:136 offset1:204
	v_mul_f32_e32 v42, 0xbfb8aa3b, v41
	v_exp_f32_e32 v42, v42
	v_add_u32_e32 v46, s83, v67
	v_add_f32_e32 v42, 1.0, v42
	v_rcp_f32_e32 v43, v42
	v_mul_f32_e32 v42, 0xbfb8aa3b, v40
	v_exp_f32_e32 v42, v42
	s_nop 0
	v_add_f32_e32 v42, 1.0, v42
	v_rcp_f32_e32 v42, v42
	s_nop 0
	v_pk_mul_f32 v[40:41], v[40:41], v[42:43]
	s_nop 0
	v_pk_mul_f32 v[42:43], v[40:41], v[40:41]
	s_nop 0
	v_add_f32_e32 v42, v43, v42
	s_nop 1
	v_mov_b32_dpp v43, v42 quad_perm:[1,0,3,2] row_mask:0xf bank_mask:0xf
	s_waitcnt lgkmcnt(0)
	v_add_f32_e32 v42, v42, v43
	s_nop 1
	v_mov_b32_dpp v43, v42 quad_perm:[2,3,0,1] row_mask:0xf bank_mask:0xf
	s_waitcnt lgkmcnt(0)
	v_add_f32_e32 v42, v42, v43
	s_nop 1
	v_mov_b32_dpp v43, v42 row_half_mirror row_mask:0xf bank_mask:0xf
	s_waitcnt lgkmcnt(0)
	v_add_f32_e32 v42, v42, v43
	s_nop 1
	v_mov_b32_dpp v43, v42 row_mirror row_mask:0xf bank_mask:0xf
	s_waitcnt lgkmcnt(0)
	v_add_f32_e32 v42, v42, v43
	v_mov_b32_e32 v43, v42
	v_mov_b32_e32 v89, v42
	s_nop 1
	v_permlane16_swap_b32_e32 v43, v89
	s_nop 1
	v_mov_b32_dpp v43, v89 quad_perm:[0,1,2,3] row_mask:0x5 bank_mask:0xf
	s_waitcnt lgkmcnt(0)
	v_add_f32_e32 v42, v42, v43
	v_mov_b32_e32 v43, v42
	v_mov_b32_e32 v89, v42
	s_nop 1
	v_permlane32_swap_b32_e32 v43, v89
	s_nop 1
	v_mov_b32_dpp v43, v89 quad_perm:[0,1,2,3] row_mask:0x3 bank_mask:0xf
	s_waitcnt lgkmcnt(0)
	v_add_f32_e32 v42, v42, v43
	v_add_f32_e32 v42, 0x358637bd, v42
	v_rsq_f32_e32 v42, v42
	s_nop 0
	v_mul_f32_e32 v42, 0x3db504f3, v42
	v_pk_mul_f32 v[40:41], v[40:41], v[42:43] op_sel_hi:[1,0]
	v_and_b32_e32 v43, 0xffff0000, v68
	v_cvt_pk_bf16_f32 v42, v40, v41
	v_mul_f32_e32 v40, 0xbfb8aa3b, v39
	v_exp_f32_e32 v40, v40
	s_nop 0
	v_add_f32_e32 v40, 1.0, v40
	v_rcp_f32_e32 v41, v40
	v_mul_f32_e32 v40, 0xbfb8aa3b, v38
	v_exp_f32_e32 v40, v40
	s_nop 0
	v_add_f32_e32 v40, 1.0, v40
	v_rcp_f32_e32 v40, v40
	s_nop 0
	v_pk_mul_f32 v[38:39], v[38:39], v[40:41]
	s_nop 0
	v_pk_mul_f32 v[40:41], v[38:39], v[38:39]
	s_nop 0
	v_add_f32_e32 v40, v41, v40
	s_nop 1
	v_mov_b32_dpp v41, v40 quad_perm:[1,0,3,2] row_mask:0xf bank_mask:0xf
	s_waitcnt lgkmcnt(0)
; #define LAS __attribute__((address_space(3)))
; DI unsigned pk2(float lo, float hi) { f32x2 v = {lo, hi}; bf16x2_t b = __builtin_convertvector(v, bf16x2_t); return __builtin_bit_cast(unsigned, b); }
; DI float siluf_(float x) { return x * __builtin_amdgcn_rcpf(1.f + __expf(-x)); }
; DI float wave_sum(float v) {
; #pragma unroll
;     for (int o = 1; o < 64; o <<= 1) v += __shfl_xor(v, o);
;     return v;
; }
; DI void gdn_prep_item(LAS unsigned char* lds, const Ctx& c, int l, int item) {
;     ...
;             for (int t = 0; t < 8; ++t) {
;                 float a0 = 0.f, a1 = 0.f;
; #pragma unroll
;                 for (int j = 0; j < 4; ++j) { a0 += w0[j] * x0[t + j]; a1 += w1[j] * x1[t + j]; }
;                 a0 = siluf_(a0); a1 = siluf_(a1);
;                 const int tl = 8 * tg + t;
;                 if (which < 2) {
;                     const float ss = wave_sum(a0 * a0 + a1 * a1); float rs = __builtin_amdgcn_rsqf(ss + RMS_EPS); if (which == 0) rs *= 0.08838834764831845f;
;                     a0 *= rs; a1 *= rs;
;                     *(LAS unsigned*)(lds + (which == 0 ? GP_QB : GP_KB) + tl * 272 + cp * 4) = pk2(a0, a1);
;                     if (which == 1) { kf[tl * 129 + 2 * cp] = a0; kf[tl * 129 + 2 * cp + 1] = a1; }
;                 } else { vf[tl * 129 + 2 * cp] = a0; vf[tl * 129 + 2 * cp + 1] = a1; }
;             }
;         }
	v_add_f32_e32 v40, v40, v41
	s_nop 1
	v_mov_b32_dpp v41, v40 quad_perm:[2,3,0,1] row_mask:0xf bank_mask:0xf
	s_waitcnt lgkmcnt(0)
	v_add_f32_e32 v40, v40, v41
	s_nop 1
	v_mov_b32_dpp v41, v40 row_half_mirror row_mask:0xf bank_mask:0xf
	s_waitcnt lgkmcnt(0)
	v_add_f32_e32 v40, v40, v41
	s_nop 1
	v_mov_b32_dpp v41, v40 row_mirror row_mask:0xf bank_mask:0xf
	s_waitcnt lgkmcnt(0)
	v_add_f32_e32 v40, v40, v41
	v_mov_b32_e32 v41, v40
	v_mov_b32_e32 v89, v40
	s_nop 1
	v_permlane16_swap_b32_e32 v41, v89
	s_nop 1
	v_mov_b32_dpp v41, v89 quad_perm:[0,1,2,3] row_mask:0x5 bank_mask:0xf
	s_waitcnt lgkmcnt(0)
	v_add_f32_e32 v40, v40, v41
	v_mov_b32_e32 v41, v40
	v_mov_b32_e32 v89, v40
	s_nop 1
	v_permlane32_swap_b32_e32 v41, v89
	s_nop 1
	v_mov_b32_dpp v41, v89 quad_perm:[0,1,2,3] row_mask:0x3 bank_mask:0xf
	s_waitcnt lgkmcnt(0)
	v_add_f32_e32 v40, v40, v41
	v_add_f32_e32 v40, 0x358637bd, v40
	v_rsq_f32_e32 v40, v40
	s_nop 0
	v_mul_f32_e32 v40, 0x3db504f3, v40
	v_pk_mul_f32 v[38:39], v[38:39], v[40:41] op_sel_hi:[1,0]
	v_lshlrev_b32_e32 v40, 16, v70
	v_cvt_pk_bf16_f32 v38, v38, v39
	v_add_u32_e32 v39, 0x400, v48
	ds_write2_b32 v39, v42, v38 offset0:16 offset1:84
	v_lshlrev_b32_e32 v42, 16, v68
	v_and_b32_e32 v41, 0xffff0000, v70
	s_waitcnt vmcnt(7)
	v_pk_fma_f32 v[42:43], v[10:11], v[42:43], 0 op_sel_hi:[1,1,0]
	v_lshlrev_b32_e32 v38, 16, v69
	v_and_b32_e32 v39, 0xffff0000, v69
	s_waitcnt vmcnt(6)
	v_pk_fma_f32 v[42:43], v[12:13], v[40:41], v[42:43]
	v_pk_fma_f32 v[40:41], v[10:11], v[40:41], 0 op_sel_hi:[1,1,0]
	s_waitcnt vmcnt(5)
	v_pk_fma_f32 v[42:43], v[14:15], v[38:39], v[42:43]
	v_pk_fma_f32 v[40:41], v[12:13], v[38:39], v[40:41]
	s_waitcnt vmcnt(4)
	v_pk_fma_f32 v[42:43], v[16:17], v[36:37], v[42:43]
	v_pk_fma_f32 v[40:41], v[14:15], v[36:37], v[40:41]
	v_mul_f32_e32 v44, 0xbfb8aa3b, v43
	v_exp_f32_e32 v44, v44
	ds_write_b32 v48, v18 offset:1632
	v_pk_fma_f32 v[40:41], v[16:17], v[34:35], v[40:41]
	v_pk_fma_f32 v[38:39], v[10:11], v[38:39], 0 op_sel_hi:[1,1,0]
	v_add_f32_e32 v44, 1.0, v44
	v_rcp_f32_e32 v45, v44
	v_mul_f32_e32 v44, 0xbfb8aa3b, v42
	v_exp_f32_e32 v44, v44
	v_pk_fma_f32 v[38:39], v[12:13], v[36:37], v[38:39]
	v_pk_fma_f32 v[36:37], v[10:11], v[36:37], 0 op_sel_hi:[1,1,0]
	v_pk_fma_f32 v[38:39], v[14:15], v[34:35], v[38:39]
	v_add_f32_e32 v44, 1.0, v44
	v_rcp_f32_e32 v44, v44
	v_pk_fma_f32 v[38:39], v[16:17], v[32:33], v[38:39]
	v_pk_fma_f32 v[36:37], v[12:13], v[34:35], v[36:37]
	v_pk_fma_f32 v[34:35], v[10:11], v[34:35], 0 op_sel_hi:[1,1,0]
	v_pk_mul_f32 v[42:43], v[42:43], v[44:45]
	v_pk_fma_f32 v[36:37], v[14:15], v[32:33], v[36:37]
	v_pk_mul_f32 v[44:45], v[42:43], v[42:43]
	v_pk_fma_f32 v[36:37], v[16:17], v[30:31], v[36:37]
	v_add_f32_e32 v44, v45, v44
	s_nop 1
	v_mov_b32_dpp v45, v44 quad_perm:[1,0,3,2] row_mask:0xf bank_mask:0xf
	v_pk_fma_f32 v[34:35], v[12:13], v[32:33], v[34:35]
	v_lshlrev_b32_e32 v18, 16, v76
	v_pk_fma_f32 v[34:35], v[14:15], v[30:31], v[34:35]
	v_pk_fma_f32 v[32:33], v[10:11], v[32:33], 0 op_sel_hi:[1,1,0]
	s_waitcnt lgkmcnt(0)
	v_add_f32_e32 v44, v44, v45
	s_nop 1
	v_mov_b32_dpp v45, v44 quad_perm:[2,3,0,1] row_mask:0xf bank_mask:0xf
	v_pk_fma_f32 v[34:35], v[16:17], v[18:19], v[34:35]
	v_pk_fma_f32 v[32:33], v[12:13], v[30:31], v[32:33]
	v_pk_fma_f32 v[30:31], v[10:11], v[30:31], 0 op_sel_hi:[1,1,0]
	v_pk_fma_f32 v[32:33], v[14:15], v[18:19], v[32:33]
	s_waitcnt lgkmcnt(0)
	v_add_f32_e32 v44, v44, v45
	s_nop 1
	v_mov_b32_dpp v45, v44 row_half_mirror row_mask:0xf bank_mask:0xf
	v_pk_fma_f32 v[32:33], v[16:17], v[20:21], v[32:33]
	v_pk_fma_f32 v[30:31], v[12:13], v[18:19], v[30:31]
	v_pk_fma_f32 v[10:11], v[10:11], v[18:19], 0 op_sel_hi:[1,1,0]
	v_pk_fma_f32 v[30:31], v[14:15], v[20:21], v[30:31]
	s_waitcnt lgkmcnt(0)
	v_add_f32_e32 v44, v44, v45
	s_nop 1
	v_mov_b32_dpp v45, v44 row_mirror row_mask:0xf bank_mask:0xf
	v_pk_fma_f32 v[30:31], v[16:17], v[22:23], v[30:31]
	v_pk_fma_f32 v[10:11], v[12:13], v[20:21], v[10:11]
	v_lshlrev_b32_e32 v20, 16, v54
	v_pk_fma_f32 v[10:11], v[14:15], v[22:23], v[10:11]
	s_waitcnt lgkmcnt(0)
	v_add_f32_e32 v44, v44, v45
	v_mov_b32_e32 v45, v44
	v_mov_b32_e32 v89, v44
	s_nop 1
	v_permlane16_swap_b32_e32 v45, v89
	s_nop 1
	v_mov_b32_dpp v45, v89 quad_perm:[0,1,2,3] row_mask:0x5 bank_mask:0xf
	v_pk_fma_f32 v[10:11], v[16:17], v[24:25], v[10:11]
	v_lshlrev_b32_e32 v22, 16, v51
	v_mul_f32_e32 v12, 0xbfb8aa3b, v11
	v_exp_f32_e32 v12, v12
	s_waitcnt lgkmcnt(0)
	v_add_f32_e32 v44, v44, v45
	v_mov_b32_e32 v45, v44
	v_mov_b32_e32 v89, v44
	s_nop 1
	v_permlane32_swap_b32_e32 v45, v89
	s_nop 1
	v_mov_b32_dpp v45, v89 quad_perm:[0,1,2,3] row_mask:0x3 bank_mask:0xf
	v_and_b32_e32 v23, 0xffff0000, v51
	v_add_f32_e32 v12, 1.0, v12
	v_rcp_f32_e32 v13, v12
	v_mul_f32_e32 v12, 0xbfb8aa3b, v10
	s_waitcnt lgkmcnt(0)
	v_add_f32_e32 v44, v44, v45
	v_add_f32_e32 v44, 0x358637bd, v44
	v_rsq_f32_e32 v44, v44
	v_exp_f32_e32 v12, v12
	v_lshlrev_b32_e32 v24, 16, v53
	v_and_b32_e32 v25, 0xffff0000, v53
	v_pk_mul_f32 v[42:43], v[42:43], v[44:45] op_sel_hi:[1,0]
	v_add_f32_e32 v12, 1.0, v12
	v_cvt_pk_bf16_f32 v44, v42, v43
	ds_write_b32 v79, v44 offset:17408
	ds_write_b64 v46, v[42:43] offset:34816
	v_add_u32_e32 v42, s4, v67
	v_add_u32_e32 v44, 0x8800, v42
	v_mul_f32_e32 v42, 0xbfb8aa3b, v41
	v_exp_f32_e32 v42, v42
	v_rcp_f32_e32 v12, v12
	v_and_b32_e32 v21, 0xffff0000, v54
	v_lshlrev_b32_e32 v18, 16, v57
	v_add_f32_e32 v42, 1.0, v42
	v_rcp_f32_e32 v43, v42
	v_mul_f32_e32 v42, 0xbfb8aa3b, v40
	v_exp_f32_e32 v42, v42
	v_pk_mul_f32 v[10:11], v[10:11], v[12:13]
	v_and_b32_e32 v19, 0xffff0000, v57
	v_pk_mul_f32 v[12:13], v[10:11], v[10:11]
	v_add_f32_e32 v42, 1.0, v42
	v_rcp_f32_e32 v42, v42
	v_add_f32_e32 v12, v13, v12
	s_nop 1
	v_mov_b32_dpp v13, v12 quad_perm:[1,0,3,2] row_mask:0xf bank_mask:0xf
	v_lshlrev_b32_e32 v14, 16, v58
	v_pk_mul_f32 v[40:41], v[40:41], v[42:43]
	v_and_b32_e32 v15, 0xffff0000, v58
	v_pk_mul_f32 v[42:43], v[40:41], v[40:41]
	s_waitcnt lgkmcnt(0)
; #define LAS __attribute__((address_space(3)))
; DI unsigned pk2(float lo, float hi) { f32x2 v = {lo, hi}; bf16x2_t b = __builtin_convertvector(v, bf16x2_t); return __builtin_bit_cast(unsigned, b); }
; DI float siluf_(float x) { return x * __builtin_amdgcn_rcpf(1.f + __expf(-x)); }
; DI float wave_sum(float v) {
; #pragma unroll
;     for (int o = 1; o < 64; o <<= 1) v += __shfl_xor(v, o);
;     return v;
; }
; DI void gdn_prep_item(LAS unsigned char* lds, const Ctx& c, int l, int item) {
;     ...
;             for (int t = 0; t < 8; ++t) {
;                 float a0 = 0.f, a1 = 0.f;
; #pragma unroll
;                 for (int j = 0; j < 4; ++j) { a0 += w0[j] * x0[t + j]; a1 += w1[j] * x1[t + j]; }
;                 a0 = siluf_(a0); a1 = siluf_(a1);
;                 const int tl = 8 * tg + t;
;                 if (which < 2) {
;                     const float ss = wave_sum(a0 * a0 + a1 * a1); float rs = __builtin_amdgcn_rsqf(ss + RMS_EPS); if (which == 0) rs *= 0.08838834764831845f;
;                     a0 *= rs; a1 *= rs;
;                     *(LAS unsigned*)(lds + (which == 0 ? GP_QB : GP_KB) + tl * 272 + cp * 4) = pk2(a0, a1);
;                     if (which == 1) { kf[tl * 129 + 2 * cp] = a0; kf[tl * 129 + 2 * cp + 1] = a1; }
;                 } else { vf[tl * 129 + 2 * cp] = a0; vf[tl * 129 + 2 * cp + 1] = a1; }
;             }
;         }
	v_add_f32_e32 v12, v12, v13
	v_add_f32_e32 v42, v43, v42
	s_nop 1
	v_mov_b32_dpp v43, v42 quad_perm:[1,0,3,2] row_mask:0xf bank_mask:0xf
	s_nop 1
	v_mov_b32_dpp v13, v12 quad_perm:[2,3,0,1] row_mask:0xf bank_mask:0xf
	v_lshlrev_b32_e32 v16, 16, v60
	v_and_b32_e32 v17, 0xffff0000, v60
	s_waitcnt lgkmcnt(0)
	v_add_f32_e32 v42, v42, v43
	s_nop 1
	v_mov_b32_dpp v43, v42 quad_perm:[2,3,0,1] row_mask:0xf bank_mask:0xf
	s_waitcnt lgkmcnt(0)
	v_add_f32_e32 v12, v12, v13
	s_nop 1
	v_mov_b32_dpp v13, v12 row_half_mirror row_mask:0xf bank_mask:0xf
	s_waitcnt lgkmcnt(0)
	v_add_f32_e32 v42, v42, v43
	s_nop 1
	v_mov_b32_dpp v43, v42 row_half_mirror row_mask:0xf bank_mask:0xf
	s_waitcnt lgkmcnt(0)
	v_add_f32_e32 v12, v12, v13
	s_nop 1
	v_mov_b32_dpp v13, v12 row_mirror row_mask:0xf bank_mask:0xf
	s_waitcnt lgkmcnt(0)
	v_add_f32_e32 v42, v42, v43
	s_nop 1
	v_mov_b32_dpp v43, v42 row_mirror row_mask:0xf bank_mask:0xf
	s_waitcnt lgkmcnt(0)
	v_add_f32_e32 v12, v12, v13
	v_mov_b32_e32 v13, v12
	v_mov_b32_e32 v89, v12
	s_nop 1
	v_permlane16_swap_b32_e32 v13, v89
	s_nop 1
	v_mov_b32_dpp v13, v89 quad_perm:[0,1,2,3] row_mask:0x5 bank_mask:0xf
	s_waitcnt lgkmcnt(0)
	v_add_f32_e32 v42, v42, v43
	v_mov_b32_e32 v43, v42
	v_mov_b32_e32 v89, v42
	s_nop 1
	v_permlane16_swap_b32_e32 v43, v89
	s_nop 1
	v_mov_b32_dpp v43, v89 quad_perm:[0,1,2,3] row_mask:0x5 bank_mask:0xf
	s_waitcnt lgkmcnt(0)
	v_add_f32_e32 v12, v12, v13
	v_mov_b32_e32 v13, v12
	v_mov_b32_e32 v89, v12
	s_nop 1
	v_permlane32_swap_b32_e32 v13, v89
	s_nop 1
	v_mov_b32_dpp v13, v89 quad_perm:[0,1,2,3] row_mask:0x3 bank_mask:0xf
	s_waitcnt lgkmcnt(0)
	v_add_f32_e32 v42, v42, v43
	v_mov_b32_e32 v43, v42
	v_mov_b32_e32 v89, v42
	s_nop 1
	v_permlane32_swap_b32_e32 v43, v89
	s_nop 1
	v_mov_b32_dpp v43, v89 quad_perm:[0,1,2,3] row_mask:0x3 bank_mask:0xf
	s_waitcnt lgkmcnt(0)
	v_add_f32_e32 v12, v12, v13
	v_add_f32_e32 v12, 0x358637bd, v12
	v_rsq_f32_e32 v12, v12
	s_waitcnt lgkmcnt(0)
	v_add_f32_e32 v42, v42, v43
	v_add_f32_e32 v42, 0x358637bd, v42
	v_rsq_f32_e32 v42, v42
	v_pk_mul_f32 v[10:11], v[10:11], v[12:13] op_sel_hi:[1,0]
	v_and_b32_e32 v13, 0xffff0000, v59
	v_cvt_pk_bf16_f32 v12, v10, v11
	v_pk_mul_f32 v[40:41], v[40:41], v[42:43] op_sel_hi:[1,0]
	ds_write2_b32 v44, v40, v41 offset1:1
	v_cvt_pk_bf16_f32 v42, v40, v41
	v_mul_f32_e32 v40, 0xbfb8aa3b, v39
	v_exp_f32_e32 v40, v40
	v_add_u32_e32 v43, s5, v67
	v_add_f32_e32 v40, 1.0, v40
	v_rcp_f32_e32 v41, v40
	v_mul_f32_e32 v40, 0xbfb8aa3b, v38
	v_exp_f32_e32 v40, v40
	s_nop 0
	v_add_f32_e32 v40, 1.0, v40
	v_rcp_f32_e32 v40, v40
	s_nop 0
	v_pk_mul_f32 v[38:39], v[38:39], v[40:41]
	s_nop 0
	v_pk_mul_f32 v[40:41], v[38:39], v[38:39]
	s_nop 0
	v_add_f32_e32 v40, v41, v40
	s_nop 1
	v_mov_b32_dpp v41, v40 quad_perm:[1,0,3,2] row_mask:0xf bank_mask:0xf
	s_waitcnt lgkmcnt(0)
	v_add_f32_e32 v40, v40, v41
	s_nop 1
	v_mov_b32_dpp v41, v40 quad_perm:[2,3,0,1] row_mask:0xf bank_mask:0xf
	s_waitcnt lgkmcnt(0)
	v_add_f32_e32 v40, v40, v41
	s_nop 1
	v_mov_b32_dpp v41, v40 row_half_mirror row_mask:0xf bank_mask:0xf
	s_waitcnt lgkmcnt(0)
	v_add_f32_e32 v40, v40, v41
	s_nop 1
	v_mov_b32_dpp v41, v40 row_mirror row_mask:0xf bank_mask:0xf
	s_waitcnt lgkmcnt(0)
	v_add_f32_e32 v40, v40, v41
	v_mov_b32_e32 v41, v40
	v_mov_b32_e32 v89, v40
	s_nop 1
	v_permlane16_swap_b32_e32 v41, v89
	s_nop 1
	v_mov_b32_dpp v41, v89 quad_perm:[0,1,2,3] row_mask:0x5 bank_mask:0xf
	s_waitcnt lgkmcnt(0)
	v_add_f32_e32 v40, v40, v41
	v_mov_b32_e32 v41, v40
	v_mov_b32_e32 v89, v40
	s_nop 1
	v_permlane32_swap_b32_e32 v41, v89
	s_nop 1
	v_mov_b32_dpp v41, v89 quad_perm:[0,1,2,3] row_mask:0x3 bank_mask:0xf
	s_waitcnt lgkmcnt(0)
	v_add_f32_e32 v40, v40, v41
	v_add_f32_e32 v40, 0x358637bd, v40
	v_rsq_f32_e32 v40, v40
	s_nop 0
	v_pk_mul_f32 v[38:39], v[38:39], v[40:41] op_sel_hi:[1,0]
	s_nop 0
	v_cvt_pk_bf16_f32 v40, v38, v39
	v_add_u32_e32 v41, 0x4400, v48
	ds_write2_b32 v41, v42, v40 offset1:68
	ds_write_b64 v43, v[38:39] offset:34816
	v_add_u32_e32 v38, s6, v67
	v_add_u32_e32 v40, 0x8800, v38
	v_mul_f32_e32 v38, 0xbfb8aa3b, v37
	v_exp_f32_e32 v38, v38
	s_nop 0
	v_add_f32_e32 v38, 1.0, v38
	v_rcp_f32_e32 v39, v38
	v_mul_f32_e32 v38, 0xbfb8aa3b, v36
	v_exp_f32_e32 v38, v38
	s_nop 0
	v_add_f32_e32 v38, 1.0, v38
	v_rcp_f32_e32 v38, v38
	s_nop 0
	v_pk_mul_f32 v[36:37], v[36:37], v[38:39]
	s_nop 0
	v_pk_mul_f32 v[38:39], v[36:37], v[36:37]
	s_nop 0
	v_add_f32_e32 v38, v39, v38
	s_nop 1
	v_mov_b32_dpp v39, v38 quad_perm:[1,0,3,2] row_mask:0xf bank_mask:0xf
	s_waitcnt lgkmcnt(0)
	v_add_f32_e32 v38, v38, v39
	s_nop 1
	v_mov_b32_dpp v39, v38 quad_perm:[2,3,0,1] row_mask:0xf bank_mask:0xf
	s_waitcnt lgkmcnt(0)
	v_add_f32_e32 v38, v38, v39
	s_nop 1
	v_mov_b32_dpp v39, v38 row_half_mirror row_mask:0xf bank_mask:0xf
	s_waitcnt lgkmcnt(0)
	v_add_f32_e32 v38, v38, v39
	s_nop 1
	v_mov_b32_dpp v39, v38 row_mirror row_mask:0xf bank_mask:0xf
	s_waitcnt lgkmcnt(0)
	v_add_f32_e32 v38, v38, v39
	v_mov_b32_e32 v39, v38
	v_mov_b32_e32 v89, v38
	s_nop 1
	v_permlane16_swap_b32_e32 v39, v89
	s_nop 1
	v_mov_b32_dpp v39, v89 quad_perm:[0,1,2,3] row_mask:0x5 bank_mask:0xf
	s_waitcnt lgkmcnt(0)
	v_add_f32_e32 v38, v38, v39
	v_mov_b32_e32 v39, v38
	v_mov_b32_e32 v89, v38
	s_nop 1
	v_permlane32_swap_b32_e32 v39, v89
	s_nop 1
	v_mov_b32_dpp v39, v89 quad_perm:[0,1,2,3] row_mask:0x3 bank_mask:0xf
	s_waitcnt lgkmcnt(0)
; #define LAS __attribute__((address_space(3)))
; DI unsigned pk2(float lo, float hi) { f32x2 v = {lo, hi}; bf16x2_t b = __builtin_convertvector(v, bf16x2_t); return __builtin_bit_cast(unsigned, b); }
; DI float siluf_(float x) { return x * __builtin_amdgcn_rcpf(1.f + __expf(-x)); }
; DI float wave_sum(float v) {
; #pragma unroll
;     for (int o = 1; o < 64; o <<= 1) v += __shfl_xor(v, o);
;     return v;
; }
; DI void gdn_prep_item(LAS unsigned char* lds, const Ctx& c, int l, int item) {
;     ...
;             for (int t = 0; t < 8; ++t) {
;                 float a0 = 0.f, a1 = 0.f;
; #pragma unroll
;                 for (int j = 0; j < 4; ++j) { a0 += w0[j] * x0[t + j]; a1 += w1[j] * x1[t + j]; }
;                 a0 = siluf_(a0); a1 = siluf_(a1);
;                 const int tl = 8 * tg + t;
;                 if (which < 2) {
;                     const float ss = wave_sum(a0 * a0 + a1 * a1); float rs = __builtin_amdgcn_rsqf(ss + RMS_EPS); if (which == 0) rs *= 0.08838834764831845f;
;                     a0 *= rs; a1 *= rs;
;                     *(LAS unsigned*)(lds + (which == 0 ? GP_QB : GP_KB) + tl * 272 + cp * 4) = pk2(a0, a1);
;                     if (which == 1) { kf[tl * 129 + 2 * cp] = a0; kf[tl * 129 + 2 * cp + 1] = a1; }
;                 } else { vf[tl * 129 + 2 * cp] = a0; vf[tl * 129 + 2 * cp + 1] = a1; }
;             }
;         }
	v_add_f32_e32 v38, v38, v39
	v_add_f32_e32 v38, 0x358637bd, v38
	v_rsq_f32_e32 v38, v38
	s_nop 0
	v_pk_mul_f32 v[36:37], v[36:37], v[38:39] op_sel_hi:[1,0]
	s_nop 0
	v_cvt_pk_bf16_f32 v38, v36, v37
	ds_write2_b32 v40, v36, v37 offset1:1
	v_mul_f32_e32 v36, 0xbfb8aa3b, v35
	v_exp_f32_e32 v36, v36
	v_add_u32_e32 v39, s7, v67
	v_add_f32_e32 v36, 1.0, v36
	v_rcp_f32_e32 v37, v36
	v_mul_f32_e32 v36, 0xbfb8aa3b, v34
	v_exp_f32_e32 v36, v36
	s_nop 0
	v_add_f32_e32 v36, 1.0, v36
	v_rcp_f32_e32 v36, v36
	s_nop 0
	v_pk_mul_f32 v[34:35], v[34:35], v[36:37]
	s_nop 0
	v_pk_mul_f32 v[36:37], v[34:35], v[34:35]
	s_nop 0
	v_add_f32_e32 v36, v37, v36
	s_nop 1
	v_mov_b32_dpp v37, v36 quad_perm:[1,0,3,2] row_mask:0xf bank_mask:0xf
	s_waitcnt lgkmcnt(0)
	v_add_f32_e32 v36, v36, v37
	s_nop 1
	v_mov_b32_dpp v37, v36 quad_perm:[2,3,0,1] row_mask:0xf bank_mask:0xf
	s_waitcnt lgkmcnt(0)
	v_add_f32_e32 v36, v36, v37
	s_nop 1
	v_mov_b32_dpp v37, v36 row_half_mirror row_mask:0xf bank_mask:0xf
	s_waitcnt lgkmcnt(0)
	v_add_f32_e32 v36, v36, v37
	s_nop 1
	v_mov_b32_dpp v37, v36 row_mirror row_mask:0xf bank_mask:0xf
	s_waitcnt lgkmcnt(0)
	v_add_f32_e32 v36, v36, v37
	v_mov_b32_e32 v37, v36
	v_mov_b32_e32 v89, v36
	s_nop 1
	v_permlane16_swap_b32_e32 v37, v89
	s_nop 1
	v_mov_b32_dpp v37, v89 quad_perm:[0,1,2,3] row_mask:0x5 bank_mask:0xf
	s_waitcnt lgkmcnt(0)
	v_add_f32_e32 v36, v36, v37
	v_mov_b32_e32 v37, v36
	v_mov_b32_e32 v89, v36
	s_nop 1
	v_permlane32_swap_b32_e32 v37, v89
	s_nop 1
	v_mov_b32_dpp v37, v89 quad_perm:[0,1,2,3] row_mask:0x3 bank_mask:0xf
	s_waitcnt lgkmcnt(0)
	v_add_f32_e32 v36, v36, v37
	v_add_f32_e32 v36, 0x358637bd, v36
	v_rsq_f32_e32 v36, v36
	s_nop 0
	v_pk_mul_f32 v[34:35], v[34:35], v[36:37] op_sel_hi:[1,0]
	s_nop 0
	v_cvt_pk_bf16_f32 v36, v34, v35
	ds_write2_b32 v41, v38, v36 offset0:136 offset1:204
	ds_write_b64 v39, v[34:35] offset:34816
	v_add_u32_e32 v34, s9, v67
	v_add_u32_e32 v36, 0x8800, v34
	v_mul_f32_e32 v34, 0xbfb8aa3b, v33
	v_exp_f32_e32 v34, v34
	v_add_u32_e32 v38, s83, v0
	v_add_f32_e32 v34, 1.0, v34
	v_rcp_f32_e32 v35, v34
	v_mul_f32_e32 v34, 0xbfb8aa3b, v32
	v_exp_f32_e32 v34, v34
	s_nop 0
	v_add_f32_e32 v34, 1.0, v34
	v_rcp_f32_e32 v34, v34
	s_nop 0
	v_pk_mul_f32 v[32:33], v[32:33], v[34:35]
	s_nop 0
	v_pk_mul_f32 v[34:35], v[32:33], v[32:33]
	s_nop 0
	v_add_f32_e32 v34, v35, v34
	s_nop 1
	v_mov_b32_dpp v35, v34 quad_perm:[1,0,3,2] row_mask:0xf bank_mask:0xf
	s_waitcnt lgkmcnt(0)
	v_add_f32_e32 v34, v34, v35
	s_nop 1
	v_mov_b32_dpp v35, v34 quad_perm:[2,3,0,1] row_mask:0xf bank_mask:0xf
	s_waitcnt lgkmcnt(0)
	v_add_f32_e32 v34, v34, v35
	s_nop 1
	v_mov_b32_dpp v35, v34 row_half_mirror row_mask:0xf bank_mask:0xf
	s_waitcnt lgkmcnt(0)
	v_add_f32_e32 v34, v34, v35
	s_nop 1
	v_mov_b32_dpp v35, v34 row_mirror row_mask:0xf bank_mask:0xf
	s_waitcnt lgkmcnt(0)
	v_add_f32_e32 v34, v34, v35
	v_mov_b32_e32 v35, v34
	v_mov_b32_e32 v89, v34
	s_nop 1
	v_permlane16_swap_b32_e32 v35, v89
	s_nop 1
	v_mov_b32_dpp v35, v89 quad_perm:[0,1,2,3] row_mask:0x5 bank_mask:0xf
	s_waitcnt lgkmcnt(0)
	v_add_f32_e32 v34, v34, v35
	v_mov_b32_e32 v35, v34
	v_mov_b32_e32 v89, v34
	s_nop 1
	v_permlane32_swap_b32_e32 v35, v89
	s_nop 1
	v_mov_b32_dpp v35, v89 quad_perm:[0,1,2,3] row_mask:0x3 bank_mask:0xf
	s_waitcnt lgkmcnt(0)
	v_add_f32_e32 v34, v34, v35
	v_add_f32_e32 v34, 0x358637bd, v34
	v_rsq_f32_e32 v34, v34
	s_nop 0
	v_pk_mul_f32 v[32:33], v[32:33], v[34:35] op_sel_hi:[1,0]
	s_nop 0
	v_cvt_pk_bf16_f32 v34, v32, v33
	ds_write2_b32 v36, v32, v33 offset1:1
	v_mul_f32_e32 v32, 0xbfb8aa3b, v31
	v_exp_f32_e32 v32, v32
	v_add_u32_e32 v35, s11, v67
	v_add_f32_e32 v32, 1.0, v32
	v_rcp_f32_e32 v33, v32
	v_mul_f32_e32 v32, 0xbfb8aa3b, v30
	v_exp_f32_e32 v32, v32
	s_nop 0
	v_add_f32_e32 v32, 1.0, v32
	v_rcp_f32_e32 v32, v32
	s_nop 0
	v_pk_mul_f32 v[30:31], v[30:31], v[32:33]
	s_nop 0
	v_pk_mul_f32 v[32:33], v[30:31], v[30:31]
	s_nop 0
	v_add_f32_e32 v32, v33, v32
	s_nop 1
	v_mov_b32_dpp v33, v32 quad_perm:[1,0,3,2] row_mask:0xf bank_mask:0xf
	s_waitcnt lgkmcnt(0)
	v_add_f32_e32 v32, v32, v33
	s_nop 1
	v_mov_b32_dpp v33, v32 quad_perm:[2,3,0,1] row_mask:0xf bank_mask:0xf
	s_waitcnt lgkmcnt(0)
	v_add_f32_e32 v32, v32, v33
	s_nop 1
	v_mov_b32_dpp v33, v32 row_half_mirror row_mask:0xf bank_mask:0xf
	s_waitcnt lgkmcnt(0)
	v_add_f32_e32 v32, v32, v33
	s_nop 1
	v_mov_b32_dpp v33, v32 row_mirror row_mask:0xf bank_mask:0xf
	s_waitcnt lgkmcnt(0)
	v_add_f32_e32 v32, v32, v33
	v_mov_b32_e32 v33, v32
	v_mov_b32_e32 v89, v32
	s_nop 1
	v_permlane16_swap_b32_e32 v33, v89
	s_nop 1
	v_mov_b32_dpp v33, v89 quad_perm:[0,1,2,3] row_mask:0x5 bank_mask:0xf
	s_waitcnt lgkmcnt(0)
	v_add_f32_e32 v32, v32, v33
	v_mov_b32_e32 v33, v32
	v_mov_b32_e32 v89, v32
	s_nop 1
	v_permlane32_swap_b32_e32 v33, v89
	s_nop 1
	v_mov_b32_dpp v33, v89 quad_perm:[0,1,2,3] row_mask:0x3 bank_mask:0xf
	s_waitcnt lgkmcnt(0)
	v_add_f32_e32 v32, v32, v33
	v_add_f32_e32 v32, 0x358637bd, v32
	v_rsq_f32_e32 v32, v32
	s_nop 0
	v_pk_mul_f32 v[30:31], v[30:31], v[32:33] op_sel_hi:[1,0]
	s_nop 0
	v_cvt_pk_bf16_f32 v32, v30, v31
	v_add_u32_e32 v33, 0x4800, v48
	ds_write2_b32 v33, v34, v32 offset0:16 offset1:84
	ds_write_b64 v35, v[30:31] offset:34816
	v_and_b32_e32 v35, 0xffff0000, v50
	v_lshlrev_b32_e32 v34, 16, v50
	v_add_u32_e32 v30, s14, v67
	s_waitcnt vmcnt(3)
	v_pk_fma_f32 v[34:35], v[2:3], v[34:35], 0 op_sel_hi:[1,1,0]
	v_add_u32_e32 v30, 0x8800, v30
	s_waitcnt vmcnt(2)
	v_pk_fma_f32 v[34:35], v[4:5], v[22:23], v[34:35]
	ds_write_b32 v48, v12 offset:19040
	ds_write2_b32 v30, v10, v11 offset1:1
	v_lshlrev_b32_e32 v30, 16, v52
	v_and_b32_e32 v31, 0xffff0000, v52
	s_waitcnt vmcnt(1)
; #define LAS __attribute__((address_space(3)))
; DI unsigned pk2(float lo, float hi) { f32x2 v = {lo, hi}; bf16x2_t b = __builtin_convertvector(v, bf16x2_t); return __builtin_bit_cast(unsigned, b); }
; DI float siluf_(float x) { return x * __builtin_amdgcn_rcpf(1.f + __expf(-x)); }
; #define BLOCK_SYNC() __syncthreads()
; DI void gdn_prep_item(LAS unsigned char* lds, const Ctx& c, int l, int item) {
;     ...
;             for (int t = 0; t < 8; ++t) {
;                 float a0 = 0.f, a1 = 0.f;
; #pragma unroll
;                 for (int j = 0; j < 4; ++j) { a0 += w0[j] * x0[t + j]; a1 += w1[j] * x1[t + j]; }
;                 a0 = siluf_(a0); a1 = siluf_(a1);
;                 const int tl = 8 * tg + t;
;                 if (which < 2) {
;                     const float ss = wave_sum(a0 * a0 + a1 * a1); float rs = __builtin_amdgcn_rsqf(ss + RMS_EPS); if (which == 0) rs *= 0.08838834764831845f;
;                     a0 *= rs; a1 *= rs;
;                     *(LAS unsigned*)(lds + (which == 0 ? GP_QB : GP_KB) + tl * 272 + cp * 4) = pk2(a0, a1);
;                     if (which == 1) { kf[tl * 129 + 2 * cp] = a0; kf[tl * 129 + 2 * cp + 1] = a1; }
;                 } else { vf[tl * 129 + 2 * cp] = a0; vf[tl * 129 + 2 * cp + 1] = a1; }
;             }
;         }
;     ...
;     BLOCK_SYNC();
;     {
;         const int mat = wave >> 2, rb = wave & 3, m16 = lane & 15, g4 = lane >> 4;
;         const LAS unsigned char* Ab = lds + (mat == 0 ? GP_KB : GP_QB) + (16 * rb + m16) * 272 + g4 * 16;
;         bf16x8 af[4];
; #pragma unroll
;         for (int ks = 0; ks < 4; ++ks) af[ks] = lds_frag16(Ab + ks * 64);
;         bf16_t* ATg = (bf16_t*)(ws + WS_AT) + cidx * 4096;
;         for (int cb = 0; cb <= rb; ++cb) {
;             f32x4 d = {0.f, 0.f, 0.f, 0.f};
;             const LAS unsigned char* Bb = lds + GP_KB + (16 * cb + m16) * 272 + g4 * 16;
; #pragma unroll
;             for (int ks = 0; ks < 4; ++ks) d = __builtin_amdgcn_mfma_f32_16x16x32_bf16(af[ks], lds_frag16(Bb + ks * 64), d, 0, 0, 0);
;             const int j = 16 * cb + m16; const float gj = gL[j];
	v_pk_fma_f32 v[34:35], v[6:7], v[24:25], v[34:35]
	v_pk_fma_f32 v[22:23], v[2:3], v[22:23], 0 op_sel_hi:[1,1,0]
	s_waitcnt vmcnt(0)
	v_pk_fma_f32 v[34:35], v[8:9], v[30:31], v[34:35]
	v_pk_fma_f32 v[22:23], v[4:5], v[24:25], v[22:23]
	v_mul_f32_e32 v36, 0xbfb8aa3b, v35
	v_exp_f32_e32 v36, v36
	v_lshlrev_b32_e32 v32, 16, v55
	v_and_b32_e32 v33, 0xffff0000, v55
	v_pk_fma_f32 v[22:23], v[6:7], v[30:31], v[22:23]
	v_add_f32_e32 v36, 1.0, v36
	v_rcp_f32_e32 v37, v36
	v_mul_f32_e32 v36, 0xbfb8aa3b, v34
	v_exp_f32_e32 v36, v36
	v_pk_fma_f32 v[22:23], v[8:9], v[32:33], v[22:23]
	v_lshlrev_b32_e32 v10, 16, v56
	v_and_b32_e32 v11, 0xffff0000, v56
	v_add_f32_e32 v36, 1.0, v36
	v_rcp_f32_e32 v36, v36
	v_lshlrev_b32_e32 v12, 16, v59
	v_pk_mul_f32 v[34:35], v[34:35], v[36:37]
	ds_write_b64 v38, v[34:35]
	v_mul_f32_e32 v34, 0xbfb8aa3b, v23
	v_exp_f32_e32 v34, v34
	v_add_u32_e32 v36, s4, v0
	v_and_b32_e32 v38, 15, v26
	v_mov_b32_e32 v54, v38
	v_add_f32_e32 v34, 1.0, v34
	v_rcp_f32_e32 v35, v34
	v_mul_f32_e32 v34, 0xbfb8aa3b, v22
	v_exp_f32_e32 v34, v34
	s_nop 0
	v_add_f32_e32 v34, 1.0, v34
	v_rcp_f32_e32 v34, v34
	s_nop 0
	v_pk_mul_f32 v[22:23], v[22:23], v[34:35]
	ds_write2_b32 v36, v22, v23 offset1:1
	v_pk_fma_f32 v[22:23], v[2:3], v[24:25], 0 op_sel_hi:[1,1,0]
	v_add_u32_e32 v34, s5, v0
	v_pk_fma_f32 v[22:23], v[4:5], v[30:31], v[22:23]
	s_cselect_b64 s[4:5], -1, 0
	v_pk_fma_f32 v[22:23], v[6:7], v[32:33], v[22:23]
	s_cmpk_lt_u32 s82, 0x100
	v_pk_fma_f32 v[22:23], v[8:9], v[20:21], v[22:23]
	s_nop 0
	v_mul_f32_e32 v24, 0xbfb8aa3b, v23
	v_exp_f32_e32 v24, v24
	s_nop 0
	v_add_f32_e32 v24, 1.0, v24
	v_rcp_f32_e32 v25, v24
	v_mul_f32_e32 v24, 0xbfb8aa3b, v22
	v_exp_f32_e32 v24, v24
	s_nop 0
	v_add_f32_e32 v24, 1.0, v24
	v_rcp_f32_e32 v24, v24
	s_nop 0
	v_pk_mul_f32 v[22:23], v[22:23], v[24:25]
	ds_write_b64 v34, v[22:23]
	v_pk_fma_f32 v[22:23], v[2:3], v[30:31], 0 op_sel_hi:[1,1,0]
	v_add_u32_e32 v34, s6, v0
	v_pk_fma_f32 v[22:23], v[4:5], v[32:33], v[22:23]
	v_add_u32_e32 v30, s7, v0
	v_pk_fma_f32 v[22:23], v[6:7], v[20:21], v[22:23]
	s_cselect_b64 s[6:7], -1, 0
	v_pk_fma_f32 v[22:23], v[8:9], v[18:19], v[22:23]
	s_nop 0
	v_mul_f32_e32 v24, 0xbfb8aa3b, v23
	v_exp_f32_e32 v24, v24
	s_nop 0
	v_add_f32_e32 v24, 1.0, v24
	v_rcp_f32_e32 v25, v24
	v_mul_f32_e32 v24, 0xbfb8aa3b, v22
	v_exp_f32_e32 v24, v24
	s_nop 0
	v_add_f32_e32 v24, 1.0, v24
	v_rcp_f32_e32 v24, v24
	s_nop 0
	v_pk_mul_f32 v[22:23], v[22:23], v[24:25]
	ds_write2_b32 v34, v22, v23 offset1:1
	v_pk_fma_f32 v[22:23], v[2:3], v[32:33], 0 op_sel_hi:[1,1,0]
	s_nop 0
	v_pk_fma_f32 v[22:23], v[4:5], v[20:21], v[22:23]
	v_pk_fma_f32 v[20:21], v[2:3], v[20:21], 0 op_sel_hi:[1,1,0]
	v_pk_fma_f32 v[22:23], v[6:7], v[18:19], v[22:23]
	v_pk_fma_f32 v[20:21], v[4:5], v[18:19], v[20:21]
	v_pk_fma_f32 v[22:23], v[8:9], v[10:11], v[22:23]
	v_pk_fma_f32 v[20:21], v[6:7], v[10:11], v[20:21]
	v_mul_f32_e32 v24, 0xbfb8aa3b, v23
	v_exp_f32_e32 v24, v24
	v_pk_fma_f32 v[20:21], v[8:9], v[12:13], v[20:21]
	v_pk_fma_f32 v[18:19], v[2:3], v[18:19], 0 op_sel_hi:[1,1,0]
	v_pk_fma_f32 v[2:3], v[2:3], v[10:11], 0 op_sel_hi:[1,1,0]
	v_add_f32_e32 v24, 1.0, v24
	v_rcp_f32_e32 v25, v24
	v_mul_f32_e32 v24, 0xbfb8aa3b, v22
	v_exp_f32_e32 v24, v24
	v_pk_fma_f32 v[18:19], v[4:5], v[10:11], v[18:19]
	v_pk_fma_f32 v[2:3], v[4:5], v[12:13], v[2:3]
	v_pk_fma_f32 v[18:19], v[6:7], v[12:13], v[18:19]
	v_add_f32_e32 v24, 1.0, v24
	v_rcp_f32_e32 v24, v24
	v_pk_fma_f32 v[2:3], v[6:7], v[14:15], v[2:3]
	v_pk_fma_f32 v[18:19], v[8:9], v[14:15], v[18:19]
	v_pk_fma_f32 v[2:3], v[8:9], v[16:17], v[2:3]
	v_pk_mul_f32 v[22:23], v[22:23], v[24:25]
	ds_write_b64 v30, v[22:23]
	v_mul_f32_e32 v22, 0xbfb8aa3b, v21
	v_exp_f32_e32 v22, v22
	v_add_u32_e32 v24, s9, v0
	v_mul_f32_e32 v4, 0xbfb8aa3b, v3
	v_exp_f32_e32 v4, v4
	v_add_f32_e32 v22, 1.0, v22
	v_rcp_f32_e32 v23, v22
	v_mul_f32_e32 v22, 0xbfb8aa3b, v20
	v_exp_f32_e32 v22, v22
	v_add_f32_e32 v4, 1.0, v4
	v_rcp_f32_e32 v5, v4
	v_mul_f32_e32 v4, 0xbfb8aa3b, v2
	v_add_f32_e32 v22, 1.0, v22
	v_rcp_f32_e32 v22, v22
	v_exp_f32_e32 v4, v4
	v_pk_mul_f32 v[20:21], v[20:21], v[22:23]
	ds_write2_b32 v24, v20, v21 offset1:1
	v_mul_f32_e32 v20, 0xbfb8aa3b, v19
	v_exp_f32_e32 v20, v20
	v_add_f32_e32 v4, 1.0, v4
	v_rcp_f32_e32 v4, v4
	v_add_u32_e32 v22, s11, v0
	v_add_f32_e32 v20, 1.0, v20
	v_rcp_f32_e32 v21, v20
	v_mul_f32_e32 v20, 0xbfb8aa3b, v18
	v_exp_f32_e32 v20, v20
	v_add_u32_e32 v0, s14, v0
	s_and_b64 s[14:15], s[6:7], exec
	v_pk_mul_f32 v[2:3], v[2:3], v[4:5]
	v_add_f32_e32 v20, 1.0, v20
	v_rcp_f32_e32 v20, v20
	s_cselect_b32 s9, 0x4400, 0
	s_lshl_b32 s11, s43, 4
	s_add_i32 s9, s9, 0
	v_pk_mul_f32 v[18:19], v[18:19], v[20:21]
	ds_write_b64 v22, v[18:19]
	ds_write2_b32 v0, v2, v3 offset1:1
	v_or_b32_e32 v0, s11, v38
	v_mul_u32_u24_e32 v0, 0x110, v0
	v_and_b32_e32 v20, 48, v26
	v_add3_u32 v0, s9, v0, v20
	s_waitcnt lgkmcnt(0)
	s_barrier
	ds_read_b128 v[2:5], v0
	ds_read_b128 v[6:9], v0 offset:64
	ds_read_b128 v[10:13], v0 offset:128
	ds_read_b128 v[14:17], v0 offset:192
	v_lshrrev_b32_e32 v0, 2, v26
	v_and_or_b32 v40, v0, 12, s11
	v_lshlrev_b32_e32 v0, 2, v40
	s_add_i32 s14, 0, 0x1cb00
	s_add_i32 s42, 0, 0x1ca00
	v_or_b32_e32 v43, 1, v40
	v_add_u32_e32 v41, s14, v0
	v_add_u32_e32 v42, s42, v0
	v_lshlrev_b32_e32 v0, 2, v43
	v_or_b32_e32 v46, 2, v40
	v_add_u32_e32 v44, s14, v0
	v_add_u32_e32 v45, s42, v0
	v_lshlrev_b32_e32 v0, 2, v46
	v_or_b32_e32 v49, 3, v40
	v_add_u32_e32 v47, s14, v0
	v_add_u32_e32 v48, s42, v0
	v_lshlrev_b32_e32 v0, 2, v49
	s_lshl_b32 s9, s43, 5
	v_add_u32_e32 v50, s14, v0
	v_add_u32_e32 v51, s42, v0
	s_add_u32 s44, s9, 32
	v_lshlrev_b32_e32 v0, 8, v38
	s_lshl_b32 s9, s43, 6
	v_or3_b32 v0, v0, s9, v20
	v_readlane_b32 s9, v254, 5
	s_or_b32 s8, s24, s8
	v_mov_b32_e32 v19, v1
	v_add_u32_e32 v52, s9, v0
	s_ashr_i32 s9, s8, 31
	s_lshl_b64 s[8:9], s[8:9], 20
	v_lshlrev_b32_e32 v0, 4, v26
	s_or_b32 s8, s8, s10
	s_lshl_b32 s10, s43, 10
	v_and_b32_e32 v39, 0x300, v0
	v_or3_b32 v0, s10, v39, v38
	v_lshlrev_b32_e32 v18, 1, v0
	s_add_u32 s10, s97, s8
	v_or_b32_e32 v0, 0x180, v18
	s_addc_u32 s11, s60, s9
	v_lshl_add_u64 v[30:31], s[10:11], 0, v[0:1]
	v_or_b32_e32 v0, 0x100, v18
	v_lshl_add_u64 v[32:33], s[10:11], 0, v[0:1]
	v_or_b32_e32 v0, 0x80, v18
	v_lshl_add_u64 v[34:35], s[10:11], 0, v[0:1]
	v_lshl_add_u64 v[36:37], s[10:11], 0, v[18:19]
	v_mul_u32_u24_e32 v18, 0x110, v38
	s_add_i32 s10, 0, 0x4400
	v_lshl_add_u32 v0, v38, 2, s14
	v_add3_u32 v53, v18, v20, s10
	s_mov_b64 s[10:11], 0
	s_branch .LBB0_280
